# v27 + residual GEMM epilogue (kind 1) hand-written: per 128-column half all 16 residual row loads and the gate/gain/scale vectors requested together, xout formed in the accumulators, row sums reduced
# speedup vs baseline: 1.0222x; 1.0132x over previous
;     static __device__ __forceinline__ void run(const f32x4 (&acc)[2][2][4][2], const Unit& u, int wr, int wc, int fr, int fq, const float* xin, float* xout, const float* gate, float gs, const float* lazy_ssq, const float* lazy_g, ...
;         const unsigned b = (unsigned)(u.pm * BM) >> 13; const unsigned row0 = u.pm * BM + wr * 64 + fr; const unsigned col0 = u.pn * BM + wc * 32 + 8 * fq;
;         float rl[2][4], sq[2][4], sqb[2][4];
; #pragma unroll
;         for (int ai = 0; ai < 2; ++ai)
; #pragma unroll
;             for (int m = 0; m < 4; ++m) { rl[ai][m] = LAZY ? __builtin_amdgcn_rsqf(lazy_ssq[row0 + ai * HALF + m * 16] * (1.0f / 1024.0f) + 1e-6f) : 1.0f; sq[ai][m] = 0.f; sqb[ai][m] = 0.f; }
; #pragma unroll
;         for (int bj = 0; bj < 2; ++bj) {
;             const unsigned col = col0 + bj * HALF;
;             f32x4 gv[2], lg[2], wv[2], w2[2];
; #pragma unroll
;             for (int n = 0; n < 2; ++n) {
;                 gv[n] = *(const f32x4*)(gate + (b * 9216u + col + 4 * n)) * gs;
;                 lg[n] = (f32x4){1.f, 1.f, 1.f, 1.f}; if (LAZY) lg[n] = *(const f32x4*)(lazy_g + col + 4 * n);
;                 wv[n] = (f32x4){0.f, 0.f, 0.f, 0.f}; w2[n] = (f32x4){1.f, 1.f, 1.f, 1.f};
;                 if (aout) { wv[n] = *(const f32x4*)(wg + col + 4 * n) * (*(const f32x4*)(wsc + (b * 9216u + col + 4 * n)) + 1.0f); if (WG2) { w2[n] = *(const f32x4*)(wg2 + col + 4 * n); wv[n] = wv[n] * w2[n]; } }
;             }
;             f32x4 xq[2][2][2];
;     ...
;             constexpr bool DEEP = !LAZY && !WG2;
;             if (DEEP) RES_LD(0, 0);
; #pragma unroll
;             for (int pp = 0; pp < 4; ++pp) {
;                 if (DEEP) { if (pp < 3) RES_LD((pp + 1) & 1, pp + 1); } else RES_LD(pp & 1, pp);
; #pragma unroll
;                 for (int j = 0; j < 2; ++j) { const int i_ = 2 * pp + j, ai = i_ >> 2, m = i_ & 3; const unsigned off = (row0 + ai * HALF + m * 16) * 1024u + col;
;                     const f32x4 xi0 = xq[pp & 1][j][0], xi1 = xq[pp & 1][j][1];
;                     f32x4 xo0 = gv[0] * acc[ai][bj][m][0], xo1 = gv[1] * acc[ai][bj][m][1];
;                     if (LAZY) { xo0 = xo0 + xi0 * lg[0] * rl[ai][m]; xo1 = xo1 + xi1 * lg[1] * rl[ai][m]; } else { xo0 = xo0 + xi0; xo1 = xo1 + xi1; }
;                     *(f32x4*)(xout + off) = xo0; *(f32x4*)(xout + off + 4) = xo1;
.LBB0_480:
	s_and_b64 vcc, exec, s[8:9]
	s_cbranch_vccz .LBB0_544
	s_cmp_gt_i32 s66, 0
	s_mov_b64 s[8:9], -1
	s_cbranch_scc0 .LBB0_542
	v_mov_b32_e32 v128, 0x20810
	ds_read_b128 v[128:131], v128
	v_mov_b32_e32 v132, 0x20820
	ds_read_b128 v[132:135], v132
	v_mov_b32_e32 v136, 0x20830
	ds_read_b128 v[136:139], v136
	v_mov_b32_e32 v140, 0x20860
	ds_read_b128 v[140:143], v140
	v_mov_b32_e32 v144, 0x20870
	ds_read_b128 v[144:147], v144
	v_mov_b32_e32 v148, 0x20880
	ds_read_b128 v[148:151], v148
	v_mov_b32_e32 v152, 0x20808
	ds_read_b32 v152, v152
	s_waitcnt lgkmcnt(0)
	v_readfirstlane_b32 s38, v128
	v_readfirstlane_b32 s39, v129
	v_readfirstlane_b32 s34, v134
	v_readfirstlane_b32 s35, v135
	v_readfirstlane_b32 s40, v136
	v_readfirstlane_b32 s41, v137
	v_readfirstlane_b32 s26, v140
	v_readfirstlane_b32 s27, v141
	v_readfirstlane_b32 s28, v142
	v_readfirstlane_b32 s29, v143
	v_readfirstlane_b32 s30, v144
	v_readfirstlane_b32 s31, v145
	v_readfirstlane_b32 s10, v148
	v_readfirstlane_b32 s11, v149
	v_readfirstlane_b32 s36, v152
	s_cmp_lg_u64 s[26:27], 0
	s_cselect_b64 vcc, exec, 0
	v_mov_b32_e32 v212, 0
	v_mov_b32_e32 v213, 0
	v_mov_b32_e32 v214, 0
	v_mov_b32_e32 v215, 0
	v_mov_b32_e32 v172, 0
	v_mov_b32_e32 v173, 0
	v_mov_b32_e32 v174, 0
	v_mov_b32_e32 v175, 0
	s_lshl_b32 s2, s63, 8
	s_lshl_b32 s3, s65, 6
	s_add_i32 s2, s2, s3
	v_or_b32_e32 v231, s2, v230
	s_lshl_b32 s3, s62, 8
	s_lshl_b32 s8, s64, 5
	s_or_b32 s3, s3, s8
	v_lshl_or_b32 v176, v229, 3, s3
	v_lshl_add_u32 v248, v231, 10, v176
	v_lshlrev_b32_e32 v249, 1, v248
	v_lshlrev_b32_e32 v248, 2, v248
	s_bfe_u32 s37, s63, 0x130005
	s_mulk_i32 s37, 0x2400
	v_add_u32_e32 v231, s37, v176
	v_lshlrev_b32_e32 v231, 2, v231
	global_load_dwordx4 v[232:235], v231, s[40:41] offset:0
	global_load_dwordx4 v[236:239], v231, s[40:41] offset:16
	s_cbranch_vccz .Lres_h0_nowv
	v_lshlrev_b32_e32 v159, 2, v176
	global_load_dwordx4 v[240:243], v159, s[28:29] offset:0
	global_load_dwordx4 v[244:247], v159, s[28:29] offset:16
	global_load_dwordx4 v[204:207], v231, s[30:31] offset:0
	global_load_dwordx4 v[208:211], v231, s[30:31] offset:16
.Lres_h0_nowv:
	s_mov_b64 s[8:9], s[34:35]
	s_mov_b64 s[42:43], s[38:39]
	global_load_dwordx4 v[128:131], v248, s[8:9] offset:0
	global_load_dwordx4 v[132:135], v248, s[8:9] offset:16
	s_add_u32 s8, s34, 0x10000
	s_addc_u32 s9, s35, 0
	global_load_dwordx4 v[136:139], v248, s[8:9] offset:0
	global_load_dwordx4 v[140:143], v248, s[8:9] offset:16
	s_add_u32 s8, s34, 0x20000
	s_addc_u32 s9, s35, 0
	global_load_dwordx4 v[144:147], v248, s[8:9] offset:0
	global_load_dwordx4 v[148:151], v248, s[8:9] offset:16
	s_add_u32 s8, s34, 0x30000
	s_addc_u32 s9, s35, 0
	global_load_dwordx4 v[152:155], v248, s[8:9] offset:0
	global_load_dwordx4 v[156:159], v248, s[8:9] offset:16
	s_add_u32 s8, s34, 0x80000
	s_addc_u32 s9, s35, 0
	global_load_dwordx4 v[180:183], v248, s[8:9] offset:0
	global_load_dwordx4 v[184:187], v248, s[8:9] offset:16
	s_add_u32 s8, s34, 0x90000
	s_addc_u32 s9, s35, 0
	global_load_dwordx4 v[188:191], v248, s[8:9] offset:0
	global_load_dwordx4 v[192:195], v248, s[8:9] offset:16
	s_add_u32 s8, s34, 0xa0000
	s_addc_u32 s9, s35, 0
	global_load_dwordx4 v[196:199], v248, s[8:9] offset:0
	global_load_dwordx4 v[200:203], v248, s[8:9] offset:16
	s_waitcnt vmcnt(14)
	v_pk_mul_f32 v[232:233], s[36:37], v[232:233] op_sel_hi:[0,1]
	v_pk_mul_f32 v[234:235], s[36:37], v[234:235] op_sel_hi:[0,1]
	v_pk_mul_f32 v[236:237], s[36:37], v[236:237] op_sel_hi:[0,1]
	v_pk_mul_f32 v[238:239], s[36:37], v[238:239] op_sel_hi:[0,1]
	s_cbranch_vccz .Lres_h0_nowv2
	v_pk_add_f32 v[204:205], v[204:205], 1.0 op_sel_hi:[1,0]
	v_pk_add_f32 v[206:207], v[206:207], 1.0 op_sel_hi:[1,0]
	v_pk_add_f32 v[208:209], v[208:209], 1.0 op_sel_hi:[1,0]
	v_pk_add_f32 v[210:211], v[210:211], 1.0 op_sel_hi:[1,0]
	v_pk_mul_f32 v[240:241], v[240:241], v[204:205]
	v_pk_mul_f32 v[242:243], v[242:243], v[206:207]
	v_pk_mul_f32 v[244:245], v[244:245], v[208:209]
	v_pk_mul_f32 v[246:247], v[246:247], v[210:211]
.Lres_h0_nowv2:
	s_add_u32 s8, s34, 0xb0000
	s_addc_u32 s9, s35, 0
	global_load_dwordx4 v[204:207], v248, s[8:9] offset:0
	global_load_dwordx4 v[208:211], v248, s[8:9] offset:16
	s_mov_b64 s[8:9], s[34:35]
	s_mov_b64 s[42:43], s[38:39]
	s_mov_b64 s[2:3], s[26:27]
	s_cbranch_vccz .Lres_h0_noa0
	s_waitcnt vmcnt(14)
	v_pk_fma_f32 v[124:125], v[232:233], v[124:125], v[128:129]
	v_pk_fma_f32 v[126:127], v[234:235], v[126:127], v[130:131]
	v_pk_fma_f32 v[120:121], v[236:237], v[120:121], v[132:133]
	v_pk_fma_f32 v[122:123], v[238:239], v[122:123], v[134:135]
	global_store_dwordx4 v248, v[124:127], s[42:43] offset:0
	global_store_dwordx4 v248, v[120:123], s[42:43] offset:16
	v_pk_mul_f32 v[128:129], v[124:125], v[240:241]
	v_pk_mul_f32 v[130:131], v[126:127], v[242:243]
	v_pk_mul_f32 v[132:133], v[120:121], v[244:245]
	v_pk_mul_f32 v[134:135], v[122:123], v[246:247]
	v_cvt_pk_bf16_f32 v128, v128, v129
	v_cvt_pk_bf16_f32 v129, v130, v131
	v_cvt_pk_bf16_f32 v130, v132, v133
	v_cvt_pk_bf16_f32 v131, v134, v135
	global_store_dwordx4 v249, v[128:131], s[2:3] offset:0
	v_mul_f32_e32 v132, v125, v125
	v_mul_f32_e32 v133, v127, v127
	v_mul_f32_e32 v134, v121, v121
	v_mul_f32_e32 v135, v123, v123
	v_fmac_f32_e32 v132, v124, v124
	v_fmac_f32_e32 v133, v126, v126
	v_fmac_f32_e32 v134, v120, v120
	v_fmac_f32_e32 v135, v122, v122
	v_add_f32_e32 v132, v132, v133
	v_add_f32_e32 v134, v134, v135
	v_add_f32_e32 v132, v132, v134
	v_add_f32_e32 v212, v212, v132
	s_branch .Lres_h0_done0
; __device__ __forceinline__ unsigned cvt_pk_bf16(float lo, float hi) { unsigned r; asm volatile("v_cvt_pk_bf16_f32 %0, %1, %2" : "=v"(r) : "v"(lo), "v"(hi)); return r; }
; #define RES_LD(buf, pp) do { _Pragma("unroll") for (int j = 0; j < 2; ++j) { const int i_ = 2 * (pp) + j; const unsigned off_ = (row0 + (i_ >> 2) * HALF + (i_ & 3) * 16) * 1024u + col; \
;                 xq[buf][j][0] = *(const f32x4*)(xin + off_); xq[buf][j][1] = *(const f32x4*)(xin + off_ + 4); } } while (0)
;     static __device__ __forceinline__ void run(const f32x4 (&acc)[2][2][4][2], const Unit& u, int wr, int wc, int fr, int fq, const float* xin, float* xout, const float* gate, float gs, const float* lazy_ssq, const float* lazy_g, ...
;     ...
;             for (int pp = 0; pp < 4; ++pp) {
;                 if (DEEP) { if (pp < 3) RES_LD((pp + 1) & 1, pp + 1); } else RES_LD(pp & 1, pp);
; #pragma unroll
;                 for (int j = 0; j < 2; ++j) { const int i_ = 2 * pp + j, ai = i_ >> 2, m = i_ & 3; const unsigned off = (row0 + ai * HALF + m * 16) * 1024u + col;
;                     const f32x4 xi0 = xq[pp & 1][j][0], xi1 = xq[pp & 1][j][1];
;                     f32x4 xo0 = gv[0] * acc[ai][bj][m][0], xo1 = gv[1] * acc[ai][bj][m][1];
;                     if (LAZY) { xo0 = xo0 + xi0 * lg[0] * rl[ai][m]; xo1 = xo1 + xi1 * lg[1] * rl[ai][m]; } else { xo0 = xo0 + xi0; xo1 = xo1 + xi1; }
;                     *(f32x4*)(xout + off) = xo0; *(f32x4*)(xout + off + 4) = xo1;
;                     if (aout) { const f32x4 a0 = xo0 * wv[0], a1 = xo1 * wv[1]; u32x4 w; w.x = cvt_pk_bf16(a0[0], a0[1]); w.y = cvt_pk_bf16(a0[2], a0[3]); w.z = cvt_pk_bf16(a1[0], a1[1]); w.w = cvt_pk_bf16(a1[2], a1[3]);
;                         *(u32x4*)(aout + off) = w;
;                         sq[ai][m] += ((xo0[0] * xo0[0] + xo0[1] * xo0[1]) + (xo0[2] * xo0[2] + xo0[3] * xo0[3])) + ((xo1[0] * xo1[0] + xo1[1] * xo1[1]) + (xo1[2] * xo1[2] + xo1[3] * xo1[3]));
.Lres_h0_noa0:
	s_waitcnt vmcnt(14)
	v_pk_fma_f32 v[124:125], v[232:233], v[124:125], v[128:129]
	v_pk_fma_f32 v[126:127], v[234:235], v[126:127], v[130:131]
	v_pk_fma_f32 v[120:121], v[236:237], v[120:121], v[132:133]
	v_pk_fma_f32 v[122:123], v[238:239], v[122:123], v[134:135]
	global_store_dwordx4 v248, v[124:127], s[42:43] offset:0
	global_store_dwordx4 v248, v[120:123], s[42:43] offset:16
.Lres_h0_done0:
	s_add_u32 s8, s34, 0x10000
	s_addc_u32 s9, s35, 0
	s_add_u32 s42, s38, 0x10000
	s_addc_u32 s43, s39, 0
	s_add_u32 s2, s26, 0x8000
	s_addc_u32 s3, s27, 0
	s_cbranch_vccz .Lres_h0_noa1
	s_waitcnt vmcnt(15)
	v_pk_fma_f32 v[108:109], v[232:233], v[108:109], v[136:137]
	v_pk_fma_f32 v[110:111], v[234:235], v[110:111], v[138:139]
	v_pk_fma_f32 v[104:105], v[236:237], v[104:105], v[140:141]
	v_pk_fma_f32 v[106:107], v[238:239], v[106:107], v[142:143]
	global_store_dwordx4 v248, v[108:111], s[42:43] offset:0
	global_store_dwordx4 v248, v[104:107], s[42:43] offset:16
	v_pk_mul_f32 v[136:137], v[108:109], v[240:241]
	v_pk_mul_f32 v[138:139], v[110:111], v[242:243]
	v_pk_mul_f32 v[140:141], v[104:105], v[244:245]
	v_pk_mul_f32 v[142:143], v[106:107], v[246:247]
	v_cvt_pk_bf16_f32 v136, v136, v137
	v_cvt_pk_bf16_f32 v137, v138, v139
	v_cvt_pk_bf16_f32 v138, v140, v141
	v_cvt_pk_bf16_f32 v139, v142, v143
	global_store_dwordx4 v249, v[136:139], s[2:3] offset:0
	v_mul_f32_e32 v140, v109, v109
	v_mul_f32_e32 v141, v111, v111
	v_mul_f32_e32 v142, v105, v105
	v_mul_f32_e32 v143, v107, v107
	v_fmac_f32_e32 v140, v108, v108
	v_fmac_f32_e32 v141, v110, v110
	v_fmac_f32_e32 v142, v104, v104
	v_fmac_f32_e32 v143, v106, v106
	v_add_f32_e32 v140, v140, v141
	v_add_f32_e32 v142, v142, v143
	v_add_f32_e32 v140, v140, v142
	v_add_f32_e32 v213, v213, v140
	s_branch .Lres_h0_done1
.Lres_h0_noa1:
	s_waitcnt vmcnt(14)
	v_pk_fma_f32 v[108:109], v[232:233], v[108:109], v[136:137]
	v_pk_fma_f32 v[110:111], v[234:235], v[110:111], v[138:139]
	v_pk_fma_f32 v[104:105], v[236:237], v[104:105], v[140:141]
	v_pk_fma_f32 v[106:107], v[238:239], v[106:107], v[142:143]
	global_store_dwordx4 v248, v[108:111], s[42:43] offset:0
	global_store_dwordx4 v248, v[104:107], s[42:43] offset:16
.Lres_h0_done1:
	s_add_u32 s8, s34, 0x20000
	s_addc_u32 s9, s35, 0
	s_add_u32 s42, s38, 0x20000
	s_addc_u32 s43, s39, 0
	s_add_u32 s2, s26, 0x10000
	s_addc_u32 s3, s27, 0
	s_cbranch_vccz .Lres_h0_noa2
	s_waitcnt vmcnt(16)
	v_pk_fma_f32 v[92:93], v[232:233], v[92:93], v[144:145]
	v_pk_fma_f32 v[94:95], v[234:235], v[94:95], v[146:147]
	v_pk_fma_f32 v[88:89], v[236:237], v[88:89], v[148:149]
	v_pk_fma_f32 v[90:91], v[238:239], v[90:91], v[150:151]
	global_store_dwordx4 v248, v[92:95], s[42:43] offset:0
	global_store_dwordx4 v248, v[88:91], s[42:43] offset:16
	v_pk_mul_f32 v[144:145], v[92:93], v[240:241]
	v_pk_mul_f32 v[146:147], v[94:95], v[242:243]
	v_pk_mul_f32 v[148:149], v[88:89], v[244:245]
	v_pk_mul_f32 v[150:151], v[90:91], v[246:247]
	v_cvt_pk_bf16_f32 v144, v144, v145
	v_cvt_pk_bf16_f32 v145, v146, v147
	v_cvt_pk_bf16_f32 v146, v148, v149
	v_cvt_pk_bf16_f32 v147, v150, v151
	global_store_dwordx4 v249, v[144:147], s[2:3] offset:0
	v_mul_f32_e32 v148, v93, v93
	v_mul_f32_e32 v149, v95, v95
	v_mul_f32_e32 v150, v89, v89
	v_mul_f32_e32 v151, v91, v91
	v_fmac_f32_e32 v148, v92, v92
	v_fmac_f32_e32 v149, v94, v94
	v_fmac_f32_e32 v150, v88, v88
	v_fmac_f32_e32 v151, v90, v90
	v_add_f32_e32 v148, v148, v149
	v_add_f32_e32 v150, v150, v151
	v_add_f32_e32 v148, v148, v150
	v_add_f32_e32 v214, v214, v148
	s_branch .Lres_h0_done2
.Lres_h0_noa2:
	s_waitcnt vmcnt(14)
	v_pk_fma_f32 v[92:93], v[232:233], v[92:93], v[144:145]
	v_pk_fma_f32 v[94:95], v[234:235], v[94:95], v[146:147]
	v_pk_fma_f32 v[88:89], v[236:237], v[88:89], v[148:149]
	v_pk_fma_f32 v[90:91], v[238:239], v[90:91], v[150:151]
	global_store_dwordx4 v248, v[92:95], s[42:43] offset:0
	global_store_dwordx4 v248, v[88:91], s[42:43] offset:16
.Lres_h0_done2:
	s_add_u32 s8, s34, 0x30000
	s_addc_u32 s9, s35, 0
	s_add_u32 s42, s38, 0x30000
	s_addc_u32 s43, s39, 0
	s_add_u32 s2, s26, 0x18000
	s_addc_u32 s3, s27, 0
	s_cbranch_vccz .Lres_h0_noa3
	s_waitcnt vmcnt(17)
	v_pk_fma_f32 v[76:77], v[232:233], v[76:77], v[152:153]
	v_pk_fma_f32 v[78:79], v[234:235], v[78:79], v[154:155]
	v_pk_fma_f32 v[72:73], v[236:237], v[72:73], v[156:157]
	v_pk_fma_f32 v[74:75], v[238:239], v[74:75], v[158:159]
	global_store_dwordx4 v248, v[76:79], s[42:43] offset:0
	global_store_dwordx4 v248, v[72:75], s[42:43] offset:16
	v_pk_mul_f32 v[152:153], v[76:77], v[240:241]
	v_pk_mul_f32 v[154:155], v[78:79], v[242:243]
	v_pk_mul_f32 v[156:157], v[72:73], v[244:245]
	v_pk_mul_f32 v[158:159], v[74:75], v[246:247]
	v_cvt_pk_bf16_f32 v152, v152, v153
	v_cvt_pk_bf16_f32 v153, v154, v155
	v_cvt_pk_bf16_f32 v154, v156, v157
	v_cvt_pk_bf16_f32 v155, v158, v159
	global_store_dwordx4 v249, v[152:155], s[2:3] offset:0
	v_mul_f32_e32 v156, v77, v77
	v_mul_f32_e32 v157, v79, v79
	v_mul_f32_e32 v158, v73, v73
	v_mul_f32_e32 v159, v75, v75
	v_fmac_f32_e32 v156, v76, v76
	v_fmac_f32_e32 v157, v78, v78
	v_fmac_f32_e32 v158, v72, v72
	v_fmac_f32_e32 v159, v74, v74
	v_add_f32_e32 v156, v156, v157
	v_add_f32_e32 v158, v158, v159
	v_add_f32_e32 v156, v156, v158
	v_add_f32_e32 v215, v215, v156
	s_branch .Lres_h0_done3
.Lres_h0_noa3:
	s_waitcnt vmcnt(14)
	v_pk_fma_f32 v[76:77], v[232:233], v[76:77], v[152:153]
	v_pk_fma_f32 v[78:79], v[234:235], v[78:79], v[154:155]
	v_pk_fma_f32 v[72:73], v[236:237], v[72:73], v[156:157]
	v_pk_fma_f32 v[74:75], v[238:239], v[74:75], v[158:159]
	global_store_dwordx4 v248, v[76:79], s[42:43] offset:0
	global_store_dwordx4 v248, v[72:75], s[42:43] offset:16
; __device__ __forceinline__ unsigned cvt_pk_bf16(float lo, float hi) { unsigned r; asm volatile("v_cvt_pk_bf16_f32 %0, %1, %2" : "=v"(r) : "v"(lo), "v"(hi)); return r; }
; #define RES_LD(buf, pp) do { _Pragma("unroll") for (int j = 0; j < 2; ++j) { const int i_ = 2 * (pp) + j; const unsigned off_ = (row0 + (i_ >> 2) * HALF + (i_ & 3) * 16) * 1024u + col; \
;                 xq[buf][j][0] = *(const f32x4*)(xin + off_); xq[buf][j][1] = *(const f32x4*)(xin + off_ + 4); } } while (0)
;     static __device__ __forceinline__ void run(const f32x4 (&acc)[2][2][4][2], const Unit& u, int wr, int wc, int fr, int fq, const float* xin, float* xout, const float* gate, float gs, const float* lazy_ssq, const float* lazy_g, ...
;     ...
;             for (int pp = 0; pp < 4; ++pp) {
;                 if (DEEP) { if (pp < 3) RES_LD((pp + 1) & 1, pp + 1); } else RES_LD(pp & 1, pp);
; #pragma unroll
;                 for (int j = 0; j < 2; ++j) { const int i_ = 2 * pp + j, ai = i_ >> 2, m = i_ & 3; const unsigned off = (row0 + ai * HALF + m * 16) * 1024u + col;
;                     const f32x4 xi0 = xq[pp & 1][j][0], xi1 = xq[pp & 1][j][1];
;                     f32x4 xo0 = gv[0] * acc[ai][bj][m][0], xo1 = gv[1] * acc[ai][bj][m][1];
;                     if (LAZY) { xo0 = xo0 + xi0 * lg[0] * rl[ai][m]; xo1 = xo1 + xi1 * lg[1] * rl[ai][m]; } else { xo0 = xo0 + xi0; xo1 = xo1 + xi1; }
;                     *(f32x4*)(xout + off) = xo0; *(f32x4*)(xout + off + 4) = xo1;
;                     if (aout) { const f32x4 a0 = xo0 * wv[0], a1 = xo1 * wv[1]; u32x4 w; w.x = cvt_pk_bf16(a0[0], a0[1]); w.y = cvt_pk_bf16(a0[2], a0[3]); w.z = cvt_pk_bf16(a1[0], a1[1]); w.w = cvt_pk_bf16(a1[2], a1[3]);
;                         *(u32x4*)(aout + off) = w;
;                         sq[ai][m] += ((xo0[0] * xo0[0] + xo0[1] * xo0[1]) + (xo0[2] * xo0[2] + xo0[3] * xo0[3])) + ((xo1[0] * xo1[0] + xo1[1] * xo1[1]) + (xo1[2] * xo1[2] + xo1[3] * xo1[3]));
.Lres_h0_done3:
	s_add_u32 s8, s34, 0x80000
	s_addc_u32 s9, s35, 0
	s_add_u32 s42, s38, 0x80000
	s_addc_u32 s43, s39, 0
	s_add_u32 s2, s26, 0x40000
	s_addc_u32 s3, s27, 0
	s_cbranch_vccz .Lres_h0_noa4
	s_waitcnt vmcnt(18)
	v_pk_fma_f32 v[60:61], v[232:233], v[60:61], v[180:181]
	v_pk_fma_f32 v[62:63], v[234:235], v[62:63], v[182:183]
	v_pk_fma_f32 v[56:57], v[236:237], v[56:57], v[184:185]
	v_pk_fma_f32 v[58:59], v[238:239], v[58:59], v[186:187]
	global_store_dwordx4 v248, v[60:63], s[42:43] offset:0
	global_store_dwordx4 v248, v[56:59], s[42:43] offset:16
	v_pk_mul_f32 v[180:181], v[60:61], v[240:241]
	v_pk_mul_f32 v[182:183], v[62:63], v[242:243]
	v_pk_mul_f32 v[184:185], v[56:57], v[244:245]
	v_pk_mul_f32 v[186:187], v[58:59], v[246:247]
	v_cvt_pk_bf16_f32 v180, v180, v181
	v_cvt_pk_bf16_f32 v181, v182, v183
	v_cvt_pk_bf16_f32 v182, v184, v185
	v_cvt_pk_bf16_f32 v183, v186, v187
	global_store_dwordx4 v249, v[180:183], s[2:3] offset:0
	v_mul_f32_e32 v184, v61, v61
	v_mul_f32_e32 v185, v63, v63
	v_mul_f32_e32 v186, v57, v57
	v_mul_f32_e32 v187, v59, v59
	v_fmac_f32_e32 v184, v60, v60
	v_fmac_f32_e32 v185, v62, v62
	v_fmac_f32_e32 v186, v56, v56
	v_fmac_f32_e32 v187, v58, v58
	v_add_f32_e32 v184, v184, v185
	v_add_f32_e32 v186, v186, v187
	v_add_f32_e32 v184, v184, v186
	v_add_f32_e32 v172, v172, v184
	s_branch .Lres_h0_done4
.Lres_h0_noa4:
	s_waitcnt vmcnt(14)
	v_pk_fma_f32 v[60:61], v[232:233], v[60:61], v[180:181]
	v_pk_fma_f32 v[62:63], v[234:235], v[62:63], v[182:183]
	v_pk_fma_f32 v[56:57], v[236:237], v[56:57], v[184:185]
	v_pk_fma_f32 v[58:59], v[238:239], v[58:59], v[186:187]
	global_store_dwordx4 v248, v[60:63], s[42:43] offset:0
	global_store_dwordx4 v248, v[56:59], s[42:43] offset:16
.Lres_h0_done4:
	s_add_u32 s8, s34, 0x90000
	s_addc_u32 s9, s35, 0
	s_add_u32 s42, s38, 0x90000
	s_addc_u32 s43, s39, 0
	s_add_u32 s2, s26, 0x48000
	s_addc_u32 s3, s27, 0
	s_cbranch_vccz .Lres_h0_noa5
	s_waitcnt vmcnt(19)
	v_pk_fma_f32 v[44:45], v[232:233], v[44:45], v[188:189]
	v_pk_fma_f32 v[46:47], v[234:235], v[46:47], v[190:191]
	v_pk_fma_f32 v[40:41], v[236:237], v[40:41], v[192:193]
	v_pk_fma_f32 v[42:43], v[238:239], v[42:43], v[194:195]
	global_store_dwordx4 v248, v[44:47], s[42:43] offset:0
	global_store_dwordx4 v248, v[40:43], s[42:43] offset:16
	v_pk_mul_f32 v[188:189], v[44:45], v[240:241]
	v_pk_mul_f32 v[190:191], v[46:47], v[242:243]
	v_pk_mul_f32 v[192:193], v[40:41], v[244:245]
	v_pk_mul_f32 v[194:195], v[42:43], v[246:247]
	v_cvt_pk_bf16_f32 v188, v188, v189
	v_cvt_pk_bf16_f32 v189, v190, v191
	v_cvt_pk_bf16_f32 v190, v192, v193
	v_cvt_pk_bf16_f32 v191, v194, v195
	global_store_dwordx4 v249, v[188:191], s[2:3] offset:0
	v_mul_f32_e32 v192, v45, v45
	v_mul_f32_e32 v193, v47, v47
	v_mul_f32_e32 v194, v41, v41
	v_mul_f32_e32 v195, v43, v43
	v_fmac_f32_e32 v192, v44, v44
	v_fmac_f32_e32 v193, v46, v46
	v_fmac_f32_e32 v194, v40, v40
	v_fmac_f32_e32 v195, v42, v42
	v_add_f32_e32 v192, v192, v193
	v_add_f32_e32 v194, v194, v195
	v_add_f32_e32 v192, v192, v194
	v_add_f32_e32 v173, v173, v192
	s_branch .Lres_h0_done5
.Lres_h0_noa5:
	s_waitcnt vmcnt(14)
	v_pk_fma_f32 v[44:45], v[232:233], v[44:45], v[188:189]
	v_pk_fma_f32 v[46:47], v[234:235], v[46:47], v[190:191]
	v_pk_fma_f32 v[40:41], v[236:237], v[40:41], v[192:193]
	v_pk_fma_f32 v[42:43], v[238:239], v[42:43], v[194:195]
	global_store_dwordx4 v248, v[44:47], s[42:43] offset:0
	global_store_dwordx4 v248, v[40:43], s[42:43] offset:16
.Lres_h0_done5:
	s_add_u32 s8, s34, 0xa0000
	s_addc_u32 s9, s35, 0
	s_add_u32 s42, s38, 0xa0000
	s_addc_u32 s43, s39, 0
	s_add_u32 s2, s26, 0x50000
	s_addc_u32 s3, s27, 0
	s_cbranch_vccz .Lres_h0_noa6
	s_waitcnt vmcnt(20)
	v_pk_fma_f32 v[28:29], v[232:233], v[28:29], v[196:197]
	v_pk_fma_f32 v[30:31], v[234:235], v[30:31], v[198:199]
	v_pk_fma_f32 v[24:25], v[236:237], v[24:25], v[200:201]
	v_pk_fma_f32 v[26:27], v[238:239], v[26:27], v[202:203]
	global_store_dwordx4 v248, v[28:31], s[42:43] offset:0
	global_store_dwordx4 v248, v[24:27], s[42:43] offset:16
	v_pk_mul_f32 v[196:197], v[28:29], v[240:241]
	v_pk_mul_f32 v[198:199], v[30:31], v[242:243]
	v_pk_mul_f32 v[200:201], v[24:25], v[244:245]
	v_pk_mul_f32 v[202:203], v[26:27], v[246:247]
	v_cvt_pk_bf16_f32 v196, v196, v197
	v_cvt_pk_bf16_f32 v197, v198, v199
	v_cvt_pk_bf16_f32 v198, v200, v201
	v_cvt_pk_bf16_f32 v199, v202, v203
	global_store_dwordx4 v249, v[196:199], s[2:3] offset:0
	v_mul_f32_e32 v200, v29, v29
	v_mul_f32_e32 v201, v31, v31
	v_mul_f32_e32 v202, v25, v25
	v_mul_f32_e32 v203, v27, v27
	v_fmac_f32_e32 v200, v28, v28
	v_fmac_f32_e32 v201, v30, v30
	v_fmac_f32_e32 v202, v24, v24
	v_fmac_f32_e32 v203, v26, v26
	v_add_f32_e32 v200, v200, v201
	v_add_f32_e32 v202, v202, v203
	v_add_f32_e32 v200, v200, v202
	v_add_f32_e32 v174, v174, v200
	s_branch .Lres_h0_done6
.Lres_h0_noa6:
	s_waitcnt vmcnt(14)
	v_pk_fma_f32 v[28:29], v[232:233], v[28:29], v[196:197]
	v_pk_fma_f32 v[30:31], v[234:235], v[30:31], v[198:199]
	v_pk_fma_f32 v[24:25], v[236:237], v[24:25], v[200:201]
	v_pk_fma_f32 v[26:27], v[238:239], v[26:27], v[202:203]
	global_store_dwordx4 v248, v[28:31], s[42:43] offset:0
	global_store_dwordx4 v248, v[24:27], s[42:43] offset:16
;     static __device__ __forceinline__ void run(const f32x4 (&acc)[2][2][4][2], const Unit& u, int wr, int wc, int fr, int fq, const float* xin, float* xout, const float* gate, float gs, const float* lazy_ssq, const float* lazy_g, ...
;     ...
;         for (int bj = 0; bj < 2; ++bj) {
;             const unsigned col = col0 + bj * HALF;
;             f32x4 gv[2], lg[2], wv[2], w2[2];
; #pragma unroll
;             for (int n = 0; n < 2; ++n) {
;                 gv[n] = *(const f32x4*)(gate + (b * 9216u + col + 4 * n)) * gs;
;                 lg[n] = (f32x4){1.f, 1.f, 1.f, 1.f}; if (LAZY) lg[n] = *(const f32x4*)(lazy_g + col + 4 * n);
;                 wv[n] = (f32x4){0.f, 0.f, 0.f, 0.f}; w2[n] = (f32x4){1.f, 1.f, 1.f, 1.f};
;                 if (aout) { wv[n] = *(const f32x4*)(wg + col + 4 * n) * (*(const f32x4*)(wsc + (b * 9216u + col + 4 * n)) + 1.0f); if (WG2) { w2[n] = *(const f32x4*)(wg2 + col + 4 * n); wv[n] = wv[n] * w2[n]; } }
;             }
;             f32x4 xq[2][2][2];
;     ...
;             constexpr bool DEEP = !LAZY && !WG2;
;             if (DEEP) RES_LD(0, 0);
; #pragma unroll
;             for (int pp = 0; pp < 4; ++pp) {
;                 if (DEEP) { if (pp < 3) RES_LD((pp + 1) & 1, pp + 1); } else RES_LD(pp & 1, pp);
; #pragma unroll
;                 for (int j = 0; j < 2; ++j) { const int i_ = 2 * pp + j, ai = i_ >> 2, m = i_ & 3; const unsigned off = (row0 + ai * HALF + m * 16) * 1024u + col;
;                     const f32x4 xi0 = xq[pp & 1][j][0], xi1 = xq[pp & 1][j][1];
;                     f32x4 xo0 = gv[0] * acc[ai][bj][m][0], xo1 = gv[1] * acc[ai][bj][m][1];
;                     if (LAZY) { xo0 = xo0 + xi0 * lg[0] * rl[ai][m]; xo1 = xo1 + xi1 * lg[1] * rl[ai][m]; } else { xo0 = xo0 + xi0; xo1 = xo1 + xi1; }
;                     *(f32x4*)(xout + off) = xo0; *(f32x4*)(xout + off + 4) = xo1;
;                     if (aout) { const f32x4 a0 = xo0 * wv[0], a1 = xo1 * wv[1]; u32x4 w; w.x = cvt_pk_bf16(a0[0], a0[1]); w.y = cvt_pk_bf16(a0[2], a0[3]); w.z = cvt_pk_bf16(a1[0], a1[1]); w.w = cvt_pk_bf16(a1[2], a1[3]);
;                         *(u32x4*)(aout + off) = w;
;                         sq[ai][m] += ((xo0[0] * xo0[0] + xo0[1] * xo0[1]) + (xo0[2] * xo0[2] + xo0[3] * xo0[3])) + ((xo1[0] * xo1[0] + xo1[1] * xo1[1]) + (xo1[2] * xo1[2] + xo1[3] * xo1[3]));
.Lres_h0_done6:
	s_add_u32 s8, s34, 0xb0000
	s_addc_u32 s9, s35, 0
	s_add_u32 s42, s38, 0xb0000
	s_addc_u32 s43, s39, 0
	s_add_u32 s2, s26, 0x58000
	s_addc_u32 s3, s27, 0
	s_cbranch_vccz .Lres_h0_noa7
	s_waitcnt vmcnt(21)
	v_pk_fma_f32 v[12:13], v[232:233], v[12:13], v[204:205]
	v_pk_fma_f32 v[14:15], v[234:235], v[14:15], v[206:207]
	v_pk_fma_f32 v[8:9], v[236:237], v[8:9], v[208:209]
	v_pk_fma_f32 v[10:11], v[238:239], v[10:11], v[210:211]
	global_store_dwordx4 v248, v[12:15], s[42:43] offset:0
	global_store_dwordx4 v248, v[8:11], s[42:43] offset:16
	v_pk_mul_f32 v[204:205], v[12:13], v[240:241]
	v_pk_mul_f32 v[206:207], v[14:15], v[242:243]
	v_pk_mul_f32 v[208:209], v[8:9], v[244:245]
	v_pk_mul_f32 v[210:211], v[10:11], v[246:247]
	v_cvt_pk_bf16_f32 v204, v204, v205
	v_cvt_pk_bf16_f32 v205, v206, v207
	v_cvt_pk_bf16_f32 v206, v208, v209
	v_cvt_pk_bf16_f32 v207, v210, v211
	global_store_dwordx4 v249, v[204:207], s[2:3] offset:0
	v_mul_f32_e32 v208, v13, v13
	v_mul_f32_e32 v209, v15, v15
	v_mul_f32_e32 v210, v9, v9
	v_mul_f32_e32 v211, v11, v11
	v_fmac_f32_e32 v208, v12, v12
	v_fmac_f32_e32 v209, v14, v14
	v_fmac_f32_e32 v210, v8, v8
	v_fmac_f32_e32 v211, v10, v10
	v_add_f32_e32 v208, v208, v209
	v_add_f32_e32 v210, v210, v211
	v_add_f32_e32 v208, v208, v210
	v_add_f32_e32 v175, v175, v208
	s_branch .Lres_h0_done7
.Lres_h0_noa7:
	s_waitcnt vmcnt(14)
	v_pk_fma_f32 v[12:13], v[232:233], v[12:13], v[204:205]
	v_pk_fma_f32 v[14:15], v[234:235], v[14:15], v[206:207]
	v_pk_fma_f32 v[8:9], v[236:237], v[8:9], v[208:209]
	v_pk_fma_f32 v[10:11], v[238:239], v[10:11], v[210:211]
	global_store_dwordx4 v248, v[12:15], s[42:43] offset:0
	global_store_dwordx4 v248, v[8:11], s[42:43] offset:16
.Lres_h0_done7:
	global_load_dwordx4 v[232:235], v231, s[40:41] offset:512
	global_load_dwordx4 v[236:239], v231, s[40:41] offset:528
	s_cbranch_vccz .Lres_h1_nowv
	v_lshlrev_b32_e32 v159, 2, v176
	global_load_dwordx4 v[240:243], v159, s[28:29] offset:512
	global_load_dwordx4 v[244:247], v159, s[28:29] offset:528
	global_load_dwordx4 v[204:207], v231, s[30:31] offset:512
	global_load_dwordx4 v[208:211], v231, s[30:31] offset:528
.Lres_h1_nowv:
	s_mov_b64 s[8:9], s[34:35]
	s_mov_b64 s[42:43], s[38:39]
	global_load_dwordx4 v[128:131], v248, s[8:9] offset:512
	global_load_dwordx4 v[132:135], v248, s[8:9] offset:528
	s_add_u32 s8, s34, 0x10000
	s_addc_u32 s9, s35, 0
	global_load_dwordx4 v[136:139], v248, s[8:9] offset:512
	global_load_dwordx4 v[140:143], v248, s[8:9] offset:528
	s_add_u32 s8, s34, 0x20000
	s_addc_u32 s9, s35, 0
	global_load_dwordx4 v[144:147], v248, s[8:9] offset:512
	global_load_dwordx4 v[148:151], v248, s[8:9] offset:528
	s_add_u32 s8, s34, 0x30000
	s_addc_u32 s9, s35, 0
	global_load_dwordx4 v[152:155], v248, s[8:9] offset:512
	global_load_dwordx4 v[156:159], v248, s[8:9] offset:528
	s_add_u32 s8, s34, 0x80000
	s_addc_u32 s9, s35, 0
	global_load_dwordx4 v[180:183], v248, s[8:9] offset:512
	global_load_dwordx4 v[184:187], v248, s[8:9] offset:528
	s_add_u32 s8, s34, 0x90000
	s_addc_u32 s9, s35, 0
	global_load_dwordx4 v[188:191], v248, s[8:9] offset:512
	global_load_dwordx4 v[192:195], v248, s[8:9] offset:528
	s_add_u32 s8, s34, 0xa0000
	s_addc_u32 s9, s35, 0
	global_load_dwordx4 v[196:199], v248, s[8:9] offset:512
	global_load_dwordx4 v[200:203], v248, s[8:9] offset:528
	s_waitcnt vmcnt(14)
	v_pk_mul_f32 v[232:233], s[36:37], v[232:233] op_sel_hi:[0,1]
	v_pk_mul_f32 v[234:235], s[36:37], v[234:235] op_sel_hi:[0,1]
	v_pk_mul_f32 v[236:237], s[36:37], v[236:237] op_sel_hi:[0,1]
	v_pk_mul_f32 v[238:239], s[36:37], v[238:239] op_sel_hi:[0,1]
	s_cbranch_vccz .Lres_h1_nowv2
	v_pk_add_f32 v[204:205], v[204:205], 1.0 op_sel_hi:[1,0]
	v_pk_add_f32 v[206:207], v[206:207], 1.0 op_sel_hi:[1,0]
	v_pk_add_f32 v[208:209], v[208:209], 1.0 op_sel_hi:[1,0]
	v_pk_add_f32 v[210:211], v[210:211], 1.0 op_sel_hi:[1,0]
	v_pk_mul_f32 v[240:241], v[240:241], v[204:205]
	v_pk_mul_f32 v[242:243], v[242:243], v[206:207]
	v_pk_mul_f32 v[244:245], v[244:245], v[208:209]
	v_pk_mul_f32 v[246:247], v[246:247], v[210:211]
.Lres_h1_nowv2:
	s_add_u32 s8, s34, 0xb0000
	s_addc_u32 s9, s35, 0
	global_load_dwordx4 v[204:207], v248, s[8:9] offset:512
	global_load_dwordx4 v[208:211], v248, s[8:9] offset:528
	s_mov_b64 s[8:9], s[34:35]
	s_mov_b64 s[42:43], s[38:39]
	s_mov_b64 s[2:3], s[26:27]
	s_cbranch_vccz .Lres_h1_noa0
	s_waitcnt vmcnt(14)
	v_pk_fma_f32 v[116:117], v[232:233], v[116:117], v[128:129]
	v_pk_fma_f32 v[118:119], v[234:235], v[118:119], v[130:131]
	v_pk_fma_f32 v[112:113], v[236:237], v[112:113], v[132:133]
	v_pk_fma_f32 v[114:115], v[238:239], v[114:115], v[134:135]
	global_store_dwordx4 v248, v[116:119], s[42:43] offset:512
	global_store_dwordx4 v248, v[112:115], s[42:43] offset:528
	v_pk_mul_f32 v[128:129], v[116:117], v[240:241]
	v_pk_mul_f32 v[130:131], v[118:119], v[242:243]
	v_pk_mul_f32 v[132:133], v[112:113], v[244:245]
	v_pk_mul_f32 v[134:135], v[114:115], v[246:247]
	v_cvt_pk_bf16_f32 v128, v128, v129
	v_cvt_pk_bf16_f32 v129, v130, v131
	v_cvt_pk_bf16_f32 v130, v132, v133
	v_cvt_pk_bf16_f32 v131, v134, v135
	global_store_dwordx4 v249, v[128:131], s[2:3] offset:256
	v_mul_f32_e32 v132, v117, v117
	v_mul_f32_e32 v133, v119, v119
	v_mul_f32_e32 v134, v113, v113
	v_mul_f32_e32 v135, v115, v115
	v_fmac_f32_e32 v132, v116, v116
	v_fmac_f32_e32 v133, v118, v118
	v_fmac_f32_e32 v134, v112, v112
	v_fmac_f32_e32 v135, v114, v114
	v_add_f32_e32 v132, v132, v133
	v_add_f32_e32 v134, v134, v135
	v_add_f32_e32 v132, v132, v134
	v_add_f32_e32 v212, v212, v132
	s_branch .Lres_h1_done0
; __device__ __forceinline__ unsigned cvt_pk_bf16(float lo, float hi) { unsigned r; asm volatile("v_cvt_pk_bf16_f32 %0, %1, %2" : "=v"(r) : "v"(lo), "v"(hi)); return r; }
; #define RES_LD(buf, pp) do { _Pragma("unroll") for (int j = 0; j < 2; ++j) { const int i_ = 2 * (pp) + j; const unsigned off_ = (row0 + (i_ >> 2) * HALF + (i_ & 3) * 16) * 1024u + col; \
;                 xq[buf][j][0] = *(const f32x4*)(xin + off_); xq[buf][j][1] = *(const f32x4*)(xin + off_ + 4); } } while (0)
;     static __device__ __forceinline__ void run(const f32x4 (&acc)[2][2][4][2], const Unit& u, int wr, int wc, int fr, int fq, const float* xin, float* xout, const float* gate, float gs, const float* lazy_ssq, const float* lazy_g, ...
;     ...
;             for (int pp = 0; pp < 4; ++pp) {
;                 if (DEEP) { if (pp < 3) RES_LD((pp + 1) & 1, pp + 1); } else RES_LD(pp & 1, pp);
; #pragma unroll
;                 for (int j = 0; j < 2; ++j) { const int i_ = 2 * pp + j, ai = i_ >> 2, m = i_ & 3; const unsigned off = (row0 + ai * HALF + m * 16) * 1024u + col;
;                     const f32x4 xi0 = xq[pp & 1][j][0], xi1 = xq[pp & 1][j][1];
;                     f32x4 xo0 = gv[0] * acc[ai][bj][m][0], xo1 = gv[1] * acc[ai][bj][m][1];
;                     if (LAZY) { xo0 = xo0 + xi0 * lg[0] * rl[ai][m]; xo1 = xo1 + xi1 * lg[1] * rl[ai][m]; } else { xo0 = xo0 + xi0; xo1 = xo1 + xi1; }
;                     *(f32x4*)(xout + off) = xo0; *(f32x4*)(xout + off + 4) = xo1;
;                     if (aout) { const f32x4 a0 = xo0 * wv[0], a1 = xo1 * wv[1]; u32x4 w; w.x = cvt_pk_bf16(a0[0], a0[1]); w.y = cvt_pk_bf16(a0[2], a0[3]); w.z = cvt_pk_bf16(a1[0], a1[1]); w.w = cvt_pk_bf16(a1[2], a1[3]);
;                         *(u32x4*)(aout + off) = w;
;                         sq[ai][m] += ((xo0[0] * xo0[0] + xo0[1] * xo0[1]) + (xo0[2] * xo0[2] + xo0[3] * xo0[3])) + ((xo1[0] * xo1[0] + xo1[1] * xo1[1]) + (xo1[2] * xo1[2] + xo1[3] * xo1[3]));
.Lres_h1_noa0:
	s_waitcnt vmcnt(14)
	v_pk_fma_f32 v[116:117], v[232:233], v[116:117], v[128:129]
	v_pk_fma_f32 v[118:119], v[234:235], v[118:119], v[130:131]
	v_pk_fma_f32 v[112:113], v[236:237], v[112:113], v[132:133]
	v_pk_fma_f32 v[114:115], v[238:239], v[114:115], v[134:135]
	global_store_dwordx4 v248, v[116:119], s[42:43] offset:512
	global_store_dwordx4 v248, v[112:115], s[42:43] offset:528
.Lres_h1_done0:
	s_add_u32 s8, s34, 0x10000
	s_addc_u32 s9, s35, 0
	s_add_u32 s42, s38, 0x10000
	s_addc_u32 s43, s39, 0
	s_add_u32 s2, s26, 0x8000
	s_addc_u32 s3, s27, 0
	s_cbranch_vccz .Lres_h1_noa1
	s_waitcnt vmcnt(15)
	v_pk_fma_f32 v[100:101], v[232:233], v[100:101], v[136:137]
	v_pk_fma_f32 v[102:103], v[234:235], v[102:103], v[138:139]
	v_pk_fma_f32 v[96:97], v[236:237], v[96:97], v[140:141]
	v_pk_fma_f32 v[98:99], v[238:239], v[98:99], v[142:143]
	global_store_dwordx4 v248, v[100:103], s[42:43] offset:512
	global_store_dwordx4 v248, v[96:99], s[42:43] offset:528
	v_pk_mul_f32 v[136:137], v[100:101], v[240:241]
	v_pk_mul_f32 v[138:139], v[102:103], v[242:243]
	v_pk_mul_f32 v[140:141], v[96:97], v[244:245]
	v_pk_mul_f32 v[142:143], v[98:99], v[246:247]
	v_cvt_pk_bf16_f32 v136, v136, v137
	v_cvt_pk_bf16_f32 v137, v138, v139
	v_cvt_pk_bf16_f32 v138, v140, v141
	v_cvt_pk_bf16_f32 v139, v142, v143
	global_store_dwordx4 v249, v[136:139], s[2:3] offset:256
	v_mul_f32_e32 v140, v101, v101
	v_mul_f32_e32 v141, v103, v103
	v_mul_f32_e32 v142, v97, v97
	v_mul_f32_e32 v143, v99, v99
	v_fmac_f32_e32 v140, v100, v100
	v_fmac_f32_e32 v141, v102, v102
	v_fmac_f32_e32 v142, v96, v96
	v_fmac_f32_e32 v143, v98, v98
	v_add_f32_e32 v140, v140, v141
	v_add_f32_e32 v142, v142, v143
	v_add_f32_e32 v140, v140, v142
	v_add_f32_e32 v213, v213, v140
	s_branch .Lres_h1_done1
.Lres_h1_noa1:
	s_waitcnt vmcnt(14)
	v_pk_fma_f32 v[100:101], v[232:233], v[100:101], v[136:137]
	v_pk_fma_f32 v[102:103], v[234:235], v[102:103], v[138:139]
	v_pk_fma_f32 v[96:97], v[236:237], v[96:97], v[140:141]
	v_pk_fma_f32 v[98:99], v[238:239], v[98:99], v[142:143]
	global_store_dwordx4 v248, v[100:103], s[42:43] offset:512
	global_store_dwordx4 v248, v[96:99], s[42:43] offset:528
.Lres_h1_done1:
	s_add_u32 s8, s34, 0x20000
	s_addc_u32 s9, s35, 0
	s_add_u32 s42, s38, 0x20000
	s_addc_u32 s43, s39, 0
	s_add_u32 s2, s26, 0x10000
	s_addc_u32 s3, s27, 0
	s_cbranch_vccz .Lres_h1_noa2
	s_waitcnt vmcnt(16)
	v_pk_fma_f32 v[84:85], v[232:233], v[84:85], v[144:145]
	v_pk_fma_f32 v[86:87], v[234:235], v[86:87], v[146:147]
	v_pk_fma_f32 v[80:81], v[236:237], v[80:81], v[148:149]
	v_pk_fma_f32 v[82:83], v[238:239], v[82:83], v[150:151]
	global_store_dwordx4 v248, v[84:87], s[42:43] offset:512
	global_store_dwordx4 v248, v[80:83], s[42:43] offset:528
	v_pk_mul_f32 v[144:145], v[84:85], v[240:241]
	v_pk_mul_f32 v[146:147], v[86:87], v[242:243]
	v_pk_mul_f32 v[148:149], v[80:81], v[244:245]
	v_pk_mul_f32 v[150:151], v[82:83], v[246:247]
	v_cvt_pk_bf16_f32 v144, v144, v145
	v_cvt_pk_bf16_f32 v145, v146, v147
	v_cvt_pk_bf16_f32 v146, v148, v149
	v_cvt_pk_bf16_f32 v147, v150, v151
	global_store_dwordx4 v249, v[144:147], s[2:3] offset:256
	v_mul_f32_e32 v148, v85, v85
	v_mul_f32_e32 v149, v87, v87
	v_mul_f32_e32 v150, v81, v81
	v_mul_f32_e32 v151, v83, v83
	v_fmac_f32_e32 v148, v84, v84
	v_fmac_f32_e32 v149, v86, v86
	v_fmac_f32_e32 v150, v80, v80
	v_fmac_f32_e32 v151, v82, v82
	v_add_f32_e32 v148, v148, v149
	v_add_f32_e32 v150, v150, v151
	v_add_f32_e32 v148, v148, v150
	v_add_f32_e32 v214, v214, v148
	s_branch .Lres_h1_done2
.Lres_h1_noa2:
	s_waitcnt vmcnt(14)
	v_pk_fma_f32 v[84:85], v[232:233], v[84:85], v[144:145]
	v_pk_fma_f32 v[86:87], v[234:235], v[86:87], v[146:147]
	v_pk_fma_f32 v[80:81], v[236:237], v[80:81], v[148:149]
	v_pk_fma_f32 v[82:83], v[238:239], v[82:83], v[150:151]
	global_store_dwordx4 v248, v[84:87], s[42:43] offset:512
	global_store_dwordx4 v248, v[80:83], s[42:43] offset:528
.Lres_h1_done2:
	s_add_u32 s8, s34, 0x30000
	s_addc_u32 s9, s35, 0
	s_add_u32 s42, s38, 0x30000
	s_addc_u32 s43, s39, 0
	s_add_u32 s2, s26, 0x18000
	s_addc_u32 s3, s27, 0
	s_cbranch_vccz .Lres_h1_noa3
	s_waitcnt vmcnt(17)
	v_pk_fma_f32 v[68:69], v[232:233], v[68:69], v[152:153]
	v_pk_fma_f32 v[70:71], v[234:235], v[70:71], v[154:155]
	v_pk_fma_f32 v[64:65], v[236:237], v[64:65], v[156:157]
	v_pk_fma_f32 v[66:67], v[238:239], v[66:67], v[158:159]
	global_store_dwordx4 v248, v[68:71], s[42:43] offset:512
	global_store_dwordx4 v248, v[64:67], s[42:43] offset:528
	v_pk_mul_f32 v[152:153], v[68:69], v[240:241]
	v_pk_mul_f32 v[154:155], v[70:71], v[242:243]
	v_pk_mul_f32 v[156:157], v[64:65], v[244:245]
	v_pk_mul_f32 v[158:159], v[66:67], v[246:247]
	v_cvt_pk_bf16_f32 v152, v152, v153
	v_cvt_pk_bf16_f32 v153, v154, v155
	v_cvt_pk_bf16_f32 v154, v156, v157
	v_cvt_pk_bf16_f32 v155, v158, v159
	global_store_dwordx4 v249, v[152:155], s[2:3] offset:256
	v_mul_f32_e32 v156, v69, v69
	v_mul_f32_e32 v157, v71, v71
	v_mul_f32_e32 v158, v65, v65
	v_mul_f32_e32 v159, v67, v67
	v_fmac_f32_e32 v156, v68, v68
	v_fmac_f32_e32 v157, v70, v70
	v_fmac_f32_e32 v158, v64, v64
	v_fmac_f32_e32 v159, v66, v66
	v_add_f32_e32 v156, v156, v157
	v_add_f32_e32 v158, v158, v159
	v_add_f32_e32 v156, v156, v158
	v_add_f32_e32 v215, v215, v156
	s_branch .Lres_h1_done3
.Lres_h1_noa3:
	s_waitcnt vmcnt(14)
	v_pk_fma_f32 v[68:69], v[232:233], v[68:69], v[152:153]
	v_pk_fma_f32 v[70:71], v[234:235], v[70:71], v[154:155]
	v_pk_fma_f32 v[64:65], v[236:237], v[64:65], v[156:157]
	v_pk_fma_f32 v[66:67], v[238:239], v[66:67], v[158:159]
	global_store_dwordx4 v248, v[68:71], s[42:43] offset:512
	global_store_dwordx4 v248, v[64:67], s[42:43] offset:528
; __device__ __forceinline__ unsigned cvt_pk_bf16(float lo, float hi) { unsigned r; asm volatile("v_cvt_pk_bf16_f32 %0, %1, %2" : "=v"(r) : "v"(lo), "v"(hi)); return r; }
; #define RES_LD(buf, pp) do { _Pragma("unroll") for (int j = 0; j < 2; ++j) { const int i_ = 2 * (pp) + j; const unsigned off_ = (row0 + (i_ >> 2) * HALF + (i_ & 3) * 16) * 1024u + col; \
;                 xq[buf][j][0] = *(const f32x4*)(xin + off_); xq[buf][j][1] = *(const f32x4*)(xin + off_ + 4); } } while (0)
;     static __device__ __forceinline__ void run(const f32x4 (&acc)[2][2][4][2], const Unit& u, int wr, int wc, int fr, int fq, const float* xin, float* xout, const float* gate, float gs, const float* lazy_ssq, const float* lazy_g, ...
;     ...
;             for (int pp = 0; pp < 4; ++pp) {
;                 if (DEEP) { if (pp < 3) RES_LD((pp + 1) & 1, pp + 1); } else RES_LD(pp & 1, pp);
; #pragma unroll
;                 for (int j = 0; j < 2; ++j) { const int i_ = 2 * pp + j, ai = i_ >> 2, m = i_ & 3; const unsigned off = (row0 + ai * HALF + m * 16) * 1024u + col;
;                     const f32x4 xi0 = xq[pp & 1][j][0], xi1 = xq[pp & 1][j][1];
;                     f32x4 xo0 = gv[0] * acc[ai][bj][m][0], xo1 = gv[1] * acc[ai][bj][m][1];
;                     if (LAZY) { xo0 = xo0 + xi0 * lg[0] * rl[ai][m]; xo1 = xo1 + xi1 * lg[1] * rl[ai][m]; } else { xo0 = xo0 + xi0; xo1 = xo1 + xi1; }
;                     *(f32x4*)(xout + off) = xo0; *(f32x4*)(xout + off + 4) = xo1;
;                     if (aout) { const f32x4 a0 = xo0 * wv[0], a1 = xo1 * wv[1]; u32x4 w; w.x = cvt_pk_bf16(a0[0], a0[1]); w.y = cvt_pk_bf16(a0[2], a0[3]); w.z = cvt_pk_bf16(a1[0], a1[1]); w.w = cvt_pk_bf16(a1[2], a1[3]);
;                         *(u32x4*)(aout + off) = w;
;                         sq[ai][m] += ((xo0[0] * xo0[0] + xo0[1] * xo0[1]) + (xo0[2] * xo0[2] + xo0[3] * xo0[3])) + ((xo1[0] * xo1[0] + xo1[1] * xo1[1]) + (xo1[2] * xo1[2] + xo1[3] * xo1[3]));
.Lres_h1_done3:
	s_add_u32 s8, s34, 0x80000
	s_addc_u32 s9, s35, 0
	s_add_u32 s42, s38, 0x80000
	s_addc_u32 s43, s39, 0
	s_add_u32 s2, s26, 0x40000
	s_addc_u32 s3, s27, 0
	s_cbranch_vccz .Lres_h1_noa4
	s_waitcnt vmcnt(18)
	v_pk_fma_f32 v[52:53], v[232:233], v[52:53], v[180:181]
	v_pk_fma_f32 v[54:55], v[234:235], v[54:55], v[182:183]
	v_pk_fma_f32 v[48:49], v[236:237], v[48:49], v[184:185]
	v_pk_fma_f32 v[50:51], v[238:239], v[50:51], v[186:187]
	global_store_dwordx4 v248, v[52:55], s[42:43] offset:512
	global_store_dwordx4 v248, v[48:51], s[42:43] offset:528
	v_pk_mul_f32 v[180:181], v[52:53], v[240:241]
	v_pk_mul_f32 v[182:183], v[54:55], v[242:243]
	v_pk_mul_f32 v[184:185], v[48:49], v[244:245]
	v_pk_mul_f32 v[186:187], v[50:51], v[246:247]
	v_cvt_pk_bf16_f32 v180, v180, v181
	v_cvt_pk_bf16_f32 v181, v182, v183
	v_cvt_pk_bf16_f32 v182, v184, v185
	v_cvt_pk_bf16_f32 v183, v186, v187
	global_store_dwordx4 v249, v[180:183], s[2:3] offset:256
	v_mul_f32_e32 v184, v53, v53
	v_mul_f32_e32 v185, v55, v55
	v_mul_f32_e32 v186, v49, v49
	v_mul_f32_e32 v187, v51, v51
	v_fmac_f32_e32 v184, v52, v52
	v_fmac_f32_e32 v185, v54, v54
	v_fmac_f32_e32 v186, v48, v48
	v_fmac_f32_e32 v187, v50, v50
	v_add_f32_e32 v184, v184, v185
	v_add_f32_e32 v186, v186, v187
	v_add_f32_e32 v184, v184, v186
	v_add_f32_e32 v172, v172, v184
	s_branch .Lres_h1_done4
.Lres_h1_noa4:
	s_waitcnt vmcnt(14)
	v_pk_fma_f32 v[52:53], v[232:233], v[52:53], v[180:181]
	v_pk_fma_f32 v[54:55], v[234:235], v[54:55], v[182:183]
	v_pk_fma_f32 v[48:49], v[236:237], v[48:49], v[184:185]
	v_pk_fma_f32 v[50:51], v[238:239], v[50:51], v[186:187]
	global_store_dwordx4 v248, v[52:55], s[42:43] offset:512
	global_store_dwordx4 v248, v[48:51], s[42:43] offset:528
.Lres_h1_done4:
	s_add_u32 s8, s34, 0x90000
	s_addc_u32 s9, s35, 0
	s_add_u32 s42, s38, 0x90000
	s_addc_u32 s43, s39, 0
	s_add_u32 s2, s26, 0x48000
	s_addc_u32 s3, s27, 0
	s_cbranch_vccz .Lres_h1_noa5
	s_waitcnt vmcnt(19)
	v_pk_fma_f32 v[36:37], v[232:233], v[36:37], v[188:189]
	v_pk_fma_f32 v[38:39], v[234:235], v[38:39], v[190:191]
	v_pk_fma_f32 v[32:33], v[236:237], v[32:33], v[192:193]
	v_pk_fma_f32 v[34:35], v[238:239], v[34:35], v[194:195]
	global_store_dwordx4 v248, v[36:39], s[42:43] offset:512
	global_store_dwordx4 v248, v[32:35], s[42:43] offset:528
	v_pk_mul_f32 v[188:189], v[36:37], v[240:241]
	v_pk_mul_f32 v[190:191], v[38:39], v[242:243]
	v_pk_mul_f32 v[192:193], v[32:33], v[244:245]
	v_pk_mul_f32 v[194:195], v[34:35], v[246:247]
	v_cvt_pk_bf16_f32 v188, v188, v189
	v_cvt_pk_bf16_f32 v189, v190, v191
	v_cvt_pk_bf16_f32 v190, v192, v193
	v_cvt_pk_bf16_f32 v191, v194, v195
	global_store_dwordx4 v249, v[188:191], s[2:3] offset:256
	v_mul_f32_e32 v192, v37, v37
	v_mul_f32_e32 v193, v39, v39
	v_mul_f32_e32 v194, v33, v33
	v_mul_f32_e32 v195, v35, v35
	v_fmac_f32_e32 v192, v36, v36
	v_fmac_f32_e32 v193, v38, v38
	v_fmac_f32_e32 v194, v32, v32
	v_fmac_f32_e32 v195, v34, v34
	v_add_f32_e32 v192, v192, v193
	v_add_f32_e32 v194, v194, v195
	v_add_f32_e32 v192, v192, v194
	v_add_f32_e32 v173, v173, v192
	s_branch .Lres_h1_done5
.Lres_h1_noa5:
	s_waitcnt vmcnt(14)
	v_pk_fma_f32 v[36:37], v[232:233], v[36:37], v[188:189]
	v_pk_fma_f32 v[38:39], v[234:235], v[38:39], v[190:191]
	v_pk_fma_f32 v[32:33], v[236:237], v[32:33], v[192:193]
	v_pk_fma_f32 v[34:35], v[238:239], v[34:35], v[194:195]
	global_store_dwordx4 v248, v[36:39], s[42:43] offset:512
	global_store_dwordx4 v248, v[32:35], s[42:43] offset:528
.Lres_h1_done5:
	s_add_u32 s8, s34, 0xa0000
	s_addc_u32 s9, s35, 0
	s_add_u32 s42, s38, 0xa0000
	s_addc_u32 s43, s39, 0
	s_add_u32 s2, s26, 0x50000
	s_addc_u32 s3, s27, 0
	s_cbranch_vccz .Lres_h1_noa6
	s_waitcnt vmcnt(20)
	v_pk_fma_f32 v[20:21], v[232:233], v[20:21], v[196:197]
	v_pk_fma_f32 v[22:23], v[234:235], v[22:23], v[198:199]
	v_pk_fma_f32 v[16:17], v[236:237], v[16:17], v[200:201]
	v_pk_fma_f32 v[18:19], v[238:239], v[18:19], v[202:203]
	global_store_dwordx4 v248, v[20:23], s[42:43] offset:512
	global_store_dwordx4 v248, v[16:19], s[42:43] offset:528
	v_pk_mul_f32 v[196:197], v[20:21], v[240:241]
	v_pk_mul_f32 v[198:199], v[22:23], v[242:243]
	v_pk_mul_f32 v[200:201], v[16:17], v[244:245]
	v_pk_mul_f32 v[202:203], v[18:19], v[246:247]
	v_cvt_pk_bf16_f32 v196, v196, v197
	v_cvt_pk_bf16_f32 v197, v198, v199
	v_cvt_pk_bf16_f32 v198, v200, v201
	v_cvt_pk_bf16_f32 v199, v202, v203
	global_store_dwordx4 v249, v[196:199], s[2:3] offset:256
	v_mul_f32_e32 v200, v21, v21
	v_mul_f32_e32 v201, v23, v23
	v_mul_f32_e32 v202, v17, v17
	v_mul_f32_e32 v203, v19, v19
	v_fmac_f32_e32 v200, v20, v20
	v_fmac_f32_e32 v201, v22, v22
	v_fmac_f32_e32 v202, v16, v16
	v_fmac_f32_e32 v203, v18, v18
	v_add_f32_e32 v200, v200, v201
	v_add_f32_e32 v202, v202, v203
	v_add_f32_e32 v200, v200, v202
	v_add_f32_e32 v174, v174, v200
	s_branch .Lres_h1_done6
;     static __device__ __forceinline__ void run(const f32x4 (&acc)[2][2][4][2], const Unit& u, int wr, int wc, int fr, int fq, const float* xin, float* xout, const float* gate, float gs, const float* lazy_ssq, const float* lazy_g, ...
;     ...
;             for (int pp = 0; pp < 4; ++pp) {
;                 if (DEEP) { if (pp < 3) RES_LD((pp + 1) & 1, pp + 1); } else RES_LD(pp & 1, pp);
; #pragma unroll
;                 for (int j = 0; j < 2; ++j) { const int i_ = 2 * pp + j, ai = i_ >> 2, m = i_ & 3; const unsigned off = (row0 + ai * HALF + m * 16) * 1024u + col;
;                     const f32x4 xi0 = xq[pp & 1][j][0], xi1 = xq[pp & 1][j][1];
;                     f32x4 xo0 = gv[0] * acc[ai][bj][m][0], xo1 = gv[1] * acc[ai][bj][m][1];
;                     if (LAZY) { xo0 = xo0 + xi0 * lg[0] * rl[ai][m]; xo1 = xo1 + xi1 * lg[1] * rl[ai][m]; } else { xo0 = xo0 + xi0; xo1 = xo1 + xi1; }
;                     *(f32x4*)(xout + off) = xo0; *(f32x4*)(xout + off + 4) = xo1;
;                     if (aout) { const f32x4 a0 = xo0 * wv[0], a1 = xo1 * wv[1]; u32x4 w; w.x = cvt_pk_bf16(a0[0], a0[1]); w.y = cvt_pk_bf16(a0[2], a0[3]); w.z = cvt_pk_bf16(a1[0], a1[1]); w.w = cvt_pk_bf16(a1[2], a1[3]);
;                         *(u32x4*)(aout + off) = w;
;                         sq[ai][m] += ((xo0[0] * xo0[0] + xo0[1] * xo0[1]) + (xo0[2] * xo0[2] + xo0[3] * xo0[3])) + ((xo1[0] * xo1[0] + xo1[1] * xo1[1]) + (xo1[2] * xo1[2] + xo1[3] * xo1[3]));
;                         if (WG2) { const f32x4 b0 = xo0 * w2[0], b1 = xo1 * w2[1]; sqb[ai][m] += ((b0[0] * b0[0] + b0[1] * b0[1]) + (b0[2] * b0[2] + b0[3] * b0[3])) + ((b1[0] * b1[0] + b1[1] * b1[1]) + (b1[2] * b1[2] + b1[3] * b1[3])); } } }
;                 asm volatile("" ::: "memory");
;             }
;     ...
;         }
;         if (aout) {
; #pragma unroll
;             for (int ai = 0; ai < 2; ++ai)
; #pragma unroll
;                 for (int m = 0; m < 4; ++m) { float s = sq[ai][m]; s = xadd<16>(s); s = xadd<32>(s);
;                     float sb = sqb[ai][m]; if (WG2) { sb = xadd<16>(sb); sb = xadd<32>(sb); }
;                     if (fq == 0) { unsafeAtomicAdd(ssq_out + (row0 + ai * HALF + m * 16), s); if (WG2) unsafeAtomicAdd(ssqB_out + (row0 + ai * HALF + m * 16), sb); } }
.Lres_h1_noa6:
	s_waitcnt vmcnt(14)
	v_pk_fma_f32 v[20:21], v[232:233], v[20:21], v[196:197]
	v_pk_fma_f32 v[22:23], v[234:235], v[22:23], v[198:199]
	v_pk_fma_f32 v[16:17], v[236:237], v[16:17], v[200:201]
	v_pk_fma_f32 v[18:19], v[238:239], v[18:19], v[202:203]
	global_store_dwordx4 v248, v[20:23], s[42:43] offset:512
	global_store_dwordx4 v248, v[16:19], s[42:43] offset:528
.Lres_h1_done6:
	s_add_u32 s8, s34, 0xb0000
	s_addc_u32 s9, s35, 0
	s_add_u32 s42, s38, 0xb0000
	s_addc_u32 s43, s39, 0
	s_add_u32 s2, s26, 0x58000
	s_addc_u32 s3, s27, 0
	s_cbranch_vccz .Lres_h1_noa7
	s_waitcnt vmcnt(21)
	v_pk_fma_f32 v[4:5], v[232:233], v[4:5], v[204:205]
	v_pk_fma_f32 v[6:7], v[234:235], v[6:7], v[206:207]
	v_pk_fma_f32 v[0:1], v[236:237], v[0:1], v[208:209]
	v_pk_fma_f32 v[2:3], v[238:239], v[2:3], v[210:211]
	global_store_dwordx4 v248, v[4:7], s[42:43] offset:512
	global_store_dwordx4 v248, v[0:3], s[42:43] offset:528
	v_pk_mul_f32 v[204:205], v[4:5], v[240:241]
	v_pk_mul_f32 v[206:207], v[6:7], v[242:243]
	v_pk_mul_f32 v[208:209], v[0:1], v[244:245]
	v_pk_mul_f32 v[210:211], v[2:3], v[246:247]
	v_cvt_pk_bf16_f32 v204, v204, v205
	v_cvt_pk_bf16_f32 v205, v206, v207
	v_cvt_pk_bf16_f32 v206, v208, v209
	v_cvt_pk_bf16_f32 v207, v210, v211
	global_store_dwordx4 v249, v[204:207], s[2:3] offset:256
	v_mul_f32_e32 v208, v5, v5
	v_mul_f32_e32 v209, v7, v7
	v_mul_f32_e32 v210, v1, v1
	v_mul_f32_e32 v211, v3, v3
	v_fmac_f32_e32 v208, v4, v4
	v_fmac_f32_e32 v209, v6, v6
	v_fmac_f32_e32 v210, v0, v0
	v_fmac_f32_e32 v211, v2, v2
	v_add_f32_e32 v208, v208, v209
	v_add_f32_e32 v210, v210, v211
	v_add_f32_e32 v208, v208, v210
	v_add_f32_e32 v175, v175, v208
	s_branch .Lres_h1_done7
.Lres_h1_noa7:
	s_waitcnt vmcnt(14)
	v_pk_fma_f32 v[4:5], v[232:233], v[4:5], v[204:205]
	v_pk_fma_f32 v[6:7], v[234:235], v[6:7], v[206:207]
	v_pk_fma_f32 v[0:1], v[236:237], v[0:1], v[208:209]
	v_pk_fma_f32 v[2:3], v[238:239], v[2:3], v[210:211]
	global_store_dwordx4 v248, v[4:7], s[42:43] offset:512
	global_store_dwordx4 v248, v[0:3], s[42:43] offset:528
.Lres_h1_done7:
	s_cbranch_vccz .Lres_noatom
	ds_swizzle_b32 v128, v212 offset:swizzle(SWAP,16)
	ds_swizzle_b32 v136, v213 offset:swizzle(SWAP,16)
	ds_swizzle_b32 v144, v214 offset:swizzle(SWAP,16)
	ds_swizzle_b32 v152, v215 offset:swizzle(SWAP,16)
	ds_swizzle_b32 v180, v172 offset:swizzle(SWAP,16)
	ds_swizzle_b32 v188, v173 offset:swizzle(SWAP,16)
	ds_swizzle_b32 v196, v174 offset:swizzle(SWAP,16)
	ds_swizzle_b32 v204, v175 offset:swizzle(SWAP,16)
	s_waitcnt lgkmcnt(0)
	v_add_f32_e32 v212, v212, v128
	v_add_f32_e32 v213, v213, v136
	v_add_f32_e32 v214, v214, v144
	v_add_f32_e32 v215, v215, v152
	v_add_f32_e32 v172, v172, v180
	v_add_f32_e32 v173, v173, v188
	v_add_f32_e32 v174, v174, v196
	v_add_f32_e32 v175, v175, v204
	v_mov_b32_e32 v128, v212
	v_mov_b32_e32 v136, v213
	v_mov_b32_e32 v144, v214
	v_mov_b32_e32 v152, v215
	v_mov_b32_e32 v180, v172
	v_mov_b32_e32 v188, v173
	v_mov_b32_e32 v196, v174
	v_mov_b32_e32 v204, v175
	s_nop 1
	v_permlane32_swap_b32_e32 v212, v128
	v_permlane32_swap_b32_e32 v213, v136
	v_permlane32_swap_b32_e32 v214, v144
	v_permlane32_swap_b32_e32 v215, v152
	v_permlane32_swap_b32_e32 v172, v180
	v_permlane32_swap_b32_e32 v173, v188
	v_permlane32_swap_b32_e32 v174, v196
	v_permlane32_swap_b32_e32 v175, v204
	s_lshl_b32 s2, s63, 8
	s_lshl_b32 s3, s65, 6
	s_add_i32 s2, s2, s3
	v_or_b32_e32 v176, s2, v230
	v_lshlrev_b32_e32 v176, 2, v176
	s_mov_b64 s[8:9], exec
	s_mov_b64 exec, 0xffff
	v_add_f32_e32 v212, v212, v128
	v_add_f32_e32 v213, v213, v136
	v_add_f32_e32 v214, v214, v144
	v_add_f32_e32 v215, v215, v152
	v_add_f32_e32 v172, v172, v180
	v_add_f32_e32 v173, v173, v188
	v_add_f32_e32 v174, v174, v196
	v_add_f32_e32 v175, v175, v204
	global_atomic_add_f32 v176, v212, s[10:11]
	global_atomic_add_f32 v176, v213, s[10:11] offset:64
	global_atomic_add_f32 v176, v214, s[10:11] offset:128
	global_atomic_add_f32 v176, v215, s[10:11] offset:192
	global_atomic_add_f32 v176, v172, s[10:11] offset:512
	global_atomic_add_f32 v176, v173, s[10:11] offset:576
	global_atomic_add_f32 v176, v174, s[10:11] offset:640
	global_atomic_add_f32 v176, v175, s[10:11] offset:704
	s_mov_b64 exec, s[8:9]
